# GEMM phases: 128 accumulator VGPRs zeroed with 64-bit moves (65 instead of 128 instructions per output tile); on top of mixer C edits
# speedup vs baseline: 1.0095x; 1.0001x over previous
; template <class Epi, class Sched, bool ALIGN_EPI = false, bool SP2 = false>
; __device__ __forceinline__ void gemm_phase(PG8_LAS unsigned char* lds, const Gemm g, const Sched& S, const Epi& E, int wave_s) {
;     ...
;         const bool has_next = S.next(ui + 1, nxt);
;         const char* nA = has_next ? (const char*)g.A + (size_t)nxt.pm * tstep : cA; const char* nB = has_next ? (const char*)g.Bt + (size_t)nxt.pn * tstep : cB;
;     ...
; #pragma unroll
;         for (int a = 0; a < 2; ++a)
; #pragma unroll
;             for (int b = 0; b < 2; ++b)
; #pragma unroll
;                 for (int m = 0; m < 4; ++m)
; #pragma unroll
;                     for (int n = 0; n < 2; ++n) acc[a][b][m][n] = (f32x4){0.f, 0.f, 0.f, 0.f};
;         cur = nxt; cA = nA; cB = nB; ++ui;
.LBB0_222:
	s_ashr_i32 s89, s88, 31
	s_lshl_b64 s[12:13], s[88:89], 19
	s_add_u32 s90, s37, s12
	s_addc_u32 s91, s38, s13
	s_and_b64 s[12:13], s[0:1], exec
	s_cselect_b32 s8, s91, s25
	s_cselect_b32 s12, s90, s24
	s_ashr_i32 s63, s62, 31
	s_lshl_b64 s[28:29], s[62:63], 19
	s_add_u32 s92, s39, s28
	s_addc_u32 s93, s40, s29
	s_and_b64 s[28:29], s[0:1], exec
	s_cselect_b32 s13, s93, s27
	s_cselect_b32 s18, s92, s26
	s_add_u32 s24, s24, 0x40080
	s_addc_u32 s25, s25, 0
	s_add_u32 s23, s26, 0x100
	v_mov_b32_e32 v2, 0
	s_addc_u32 s30, s27, 0
	s_mov_b32 s31, -2
	v_mov_b32_e32 v3, v2
	v_mov_b64_e32 v[4:5], v[2:3]
	v_mov_b64_e32 v[6:7], v[2:3]
	v_mov_b64_e32 v[8:9], v[2:3]
	v_mov_b64_e32 v[10:11], v[2:3]
	v_mov_b64_e32 v[12:13], v[2:3]
	v_mov_b64_e32 v[14:15], v[2:3]
	v_mov_b64_e32 v[16:17], v[2:3]
	v_mov_b64_e32 v[18:19], v[2:3]
	v_mov_b64_e32 v[20:21], v[2:3]
	v_mov_b64_e32 v[22:23], v[2:3]
	v_mov_b64_e32 v[24:25], v[2:3]
	v_mov_b64_e32 v[26:27], v[2:3]
	v_mov_b64_e32 v[28:29], v[2:3]
	v_mov_b64_e32 v[30:31], v[2:3]
	v_mov_b64_e32 v[32:33], v[2:3]
	v_mov_b64_e32 v[34:35], v[2:3]
	v_mov_b64_e32 v[36:37], v[2:3]
	v_mov_b64_e32 v[38:39], v[2:3]
	v_mov_b64_e32 v[40:41], v[2:3]
	v_mov_b64_e32 v[42:43], v[2:3]
	v_mov_b64_e32 v[44:45], v[2:3]
	v_mov_b64_e32 v[46:47], v[2:3]
	v_mov_b64_e32 v[48:49], v[2:3]
	v_mov_b64_e32 v[50:51], v[2:3]
	v_mov_b64_e32 v[52:53], v[2:3]
	v_mov_b64_e32 v[54:55], v[2:3]
	v_mov_b64_e32 v[56:57], v[2:3]
	v_mov_b64_e32 v[58:59], v[2:3]
	v_mov_b64_e32 v[60:61], v[2:3]
	v_mov_b64_e32 v[62:63], v[2:3]
	v_mov_b64_e32 v[64:65], v[2:3]
	v_mov_b64_e32 v[66:67], v[2:3]
	v_mov_b64_e32 v[68:69], v[2:3]
	v_mov_b64_e32 v[70:71], v[2:3]
	v_mov_b64_e32 v[72:73], v[2:3]
	v_mov_b64_e32 v[74:75], v[2:3]
	v_mov_b64_e32 v[76:77], v[2:3]
	v_mov_b64_e32 v[78:79], v[2:3]
	v_mov_b64_e32 v[80:81], v[2:3]
	v_mov_b64_e32 v[82:83], v[2:3]
	v_mov_b64_e32 v[84:85], v[2:3]
	v_mov_b64_e32 v[86:87], v[2:3]
	v_mov_b64_e32 v[88:89], v[2:3]
	v_mov_b64_e32 v[90:91], v[2:3]
	v_mov_b64_e32 v[92:93], v[2:3]
	v_mov_b64_e32 v[94:95], v[2:3]
	v_mov_b64_e32 v[96:97], v[2:3]
	v_mov_b64_e32 v[98:99], v[2:3]
	v_mov_b64_e32 v[100:101], v[2:3]
	v_mov_b64_e32 v[102:103], v[2:3]
	v_mov_b64_e32 v[104:105], v[2:3]
	v_mov_b64_e32 v[106:107], v[2:3]
	v_mov_b64_e32 v[108:109], v[2:3]
	v_mov_b64_e32 v[110:111], v[2:3]
	v_mov_b64_e32 v[112:113], v[2:3]
	v_mov_b64_e32 v[114:115], v[2:3]
	v_mov_b64_e32 v[116:117], v[2:3]
	v_mov_b64_e32 v[118:119], v[2:3]
	v_mov_b64_e32 v[120:121], v[2:3]
	v_mov_b64_e32 v[122:123], v[2:3]
	v_mov_b64_e32 v[124:125], v[2:3]
	v_mov_b64_e32 v[126:127], v[2:3]
	v_mov_b64_e32 v[128:129], v[2:3]

; template <class Epi, class Sched, bool ALIGN_EPI = false, bool SP2 = false>
; __device__ __forceinline__ void gemm_phase(PG8_LAS unsigned char* lds, const Gemm g, const Sched& S, const Epi& E, int wave_s) {
;     ...
;         const bool has_next = S.next(ui + 1, nxt);
;         const char* nA = has_next ? (const char*)g.A + (size_t)nxt.pm * tstep : cA; const char* nB = has_next ? (const char*)g.Bt + (size_t)nxt.pn * tstep : cB;
;     ...
; #pragma unroll
;         for (int a = 0; a < 2; ++a)
; #pragma unroll
;             for (int b = 0; b < 2; ++b)
; #pragma unroll
;                 for (int m = 0; m < 4; ++m)
; #pragma unroll
;                     for (int n = 0; n < 2; ++n) acc[a][b][m][n] = (f32x4){0.f, 0.f, 0.f, 0.f};
;         cur = nxt; cA = nA; cB = nB; ++ui;
.LBB0_256:
	s_ashr_i32 s93, s92, 31
	s_lshl_b64 s[28:29], s[92:93], 19
	s_add_u32 s94, s13, s28
	s_addc_u32 s95, s16, s29
	s_and_b64 s[28:29], s[0:1], exec
	s_cselect_b32 s30, s95, s25
	s_cselect_b32 s31, s94, s24
	s_ashr_i32 s91, s90, 31
	s_lshl_b64 s[28:29], s[90:91], 19
	s_add_u32 s96, s18, s28
	s_addc_u32 s97, s40, s29
	s_and_b64 s[28:29], s[0:1], exec
	s_cselect_b32 s34, s97, s27
	s_cselect_b32 s35, s96, s26
	s_add_u32 s24, s24, 0x40080
	s_addc_u32 s25, s25, 0
	s_add_u32 s36, s26, 0x100
	v_mov_b32_e32 v2, 0
	s_addc_u32 s37, s27, 0
	s_mov_b32 s38, -2
	v_mov_b32_e32 v3, v2
	v_mov_b64_e32 v[4:5], v[2:3]
	v_mov_b64_e32 v[6:7], v[2:3]
	v_mov_b64_e32 v[8:9], v[2:3]
	v_mov_b64_e32 v[10:11], v[2:3]
	v_mov_b64_e32 v[12:13], v[2:3]
	v_mov_b64_e32 v[14:15], v[2:3]
	v_mov_b64_e32 v[16:17], v[2:3]
	v_mov_b64_e32 v[18:19], v[2:3]
	v_mov_b64_e32 v[20:21], v[2:3]
	v_mov_b64_e32 v[22:23], v[2:3]
	v_mov_b64_e32 v[24:25], v[2:3]
	v_mov_b64_e32 v[26:27], v[2:3]
	v_mov_b64_e32 v[28:29], v[2:3]
	v_mov_b64_e32 v[30:31], v[2:3]
	v_mov_b64_e32 v[32:33], v[2:3]
	v_mov_b64_e32 v[34:35], v[2:3]
	v_mov_b64_e32 v[36:37], v[2:3]
	v_mov_b64_e32 v[38:39], v[2:3]
	v_mov_b64_e32 v[40:41], v[2:3]
	v_mov_b64_e32 v[42:43], v[2:3]
	v_mov_b64_e32 v[44:45], v[2:3]
	v_mov_b64_e32 v[46:47], v[2:3]
	v_mov_b64_e32 v[48:49], v[2:3]
	v_mov_b64_e32 v[50:51], v[2:3]
	v_mov_b64_e32 v[52:53], v[2:3]
	v_mov_b64_e32 v[54:55], v[2:3]
	v_mov_b64_e32 v[56:57], v[2:3]
	v_mov_b64_e32 v[58:59], v[2:3]
	v_mov_b64_e32 v[60:61], v[2:3]
	v_mov_b64_e32 v[62:63], v[2:3]
	v_mov_b64_e32 v[64:65], v[2:3]
	v_mov_b64_e32 v[66:67], v[2:3]
	v_mov_b64_e32 v[68:69], v[2:3]
	v_mov_b64_e32 v[70:71], v[2:3]
	v_mov_b64_e32 v[72:73], v[2:3]
	v_mov_b64_e32 v[74:75], v[2:3]
	v_mov_b64_e32 v[76:77], v[2:3]
	v_mov_b64_e32 v[78:79], v[2:3]
	v_mov_b64_e32 v[80:81], v[2:3]
	v_mov_b64_e32 v[82:83], v[2:3]
	v_mov_b64_e32 v[84:85], v[2:3]
	v_mov_b64_e32 v[86:87], v[2:3]
	v_mov_b64_e32 v[88:89], v[2:3]
	v_mov_b64_e32 v[90:91], v[2:3]
	v_mov_b64_e32 v[92:93], v[2:3]
	v_mov_b64_e32 v[94:95], v[2:3]
	v_mov_b64_e32 v[96:97], v[2:3]
	v_mov_b64_e32 v[98:99], v[2:3]
	v_mov_b64_e32 v[100:101], v[2:3]
	v_mov_b64_e32 v[102:103], v[2:3]
	v_mov_b64_e32 v[104:105], v[2:3]
	v_mov_b64_e32 v[106:107], v[2:3]
	v_mov_b64_e32 v[108:109], v[2:3]
	v_mov_b64_e32 v[110:111], v[2:3]
	v_mov_b64_e32 v[112:113], v[2:3]
	v_mov_b64_e32 v[114:115], v[2:3]
	v_mov_b64_e32 v[116:117], v[2:3]
	v_mov_b64_e32 v[118:119], v[2:3]
	v_mov_b64_e32 v[120:121], v[2:3]
	v_mov_b64_e32 v[122:123], v[2:3]
	v_mov_b64_e32 v[124:125], v[2:3]
	v_mov_b64_e32 v[126:127], v[2:3]
	v_mov_b64_e32 v[128:129], v[2:3]

; template <class Epi, class Sched, bool ALIGN_EPI = false, bool SP2 = false>
; __device__ __forceinline__ void gemm_phase(PG8_LAS unsigned char* lds, const Gemm g, const Sched& S, const Epi& E, int wave_s) {
;     ...
;         const bool has_next = S.next(ui + 1, nxt);
;         const char* nA = has_next ? (const char*)g.A + (size_t)nxt.pm * tstep : cA; const char* nB = has_next ? (const char*)g.Bt + (size_t)nxt.pn * tstep : cB;
;     ...
; #pragma unroll
;         for (int a = 0; a < 2; ++a)
; #pragma unroll
;             for (int b = 0; b < 2; ++b)
; #pragma unroll
;                 for (int m = 0; m < 4; ++m)
; #pragma unroll
;                     for (int n = 0; n < 2; ++n) acc[a][b][m][n] = (f32x4){0.f, 0.f, 0.f, 0.f};
;         cur = nxt; cA = nA; cB = nB; ++ui;
.LBB0_286:
	s_ashr_i32 s73, s72, 31
	s_lshl_b64 s[26:27], s[72:73], 19
	s_add_u32 s96, s41, s26
	s_addc_u32 s97, s42, s27
	s_and_b64 s[26:27], s[0:1], exec
	s_cselect_b32 s13, s97, s25
	s_cselect_b32 s23, s96, s24
	s_ashr_i32 s93, s92, 31
	s_lshl_b64 s[26:27], s[92:93], 19
	s_add_u32 s58, s43, s26
	s_addc_u32 s59, s44, s27
	s_and_b64 s[26:27], s[0:1], exec
	s_cselect_b32 s30, s59, s7
	s_cselect_b32 s31, s58, s6
	s_add_u32 s24, s24, 0x40080
	s_addc_u32 s25, s25, 0
	s_add_u32 s34, s6, 0x100
	v_mov_b32_e32 v2, 0
	s_addc_u32 s35, s7, 0
	s_mov_b32 s36, -2
	v_mov_b32_e32 v3, v2
	v_mov_b64_e32 v[4:5], v[2:3]
	v_mov_b64_e32 v[6:7], v[2:3]
	v_mov_b64_e32 v[8:9], v[2:3]
	v_mov_b64_e32 v[10:11], v[2:3]
	v_mov_b64_e32 v[12:13], v[2:3]
	v_mov_b64_e32 v[14:15], v[2:3]
	v_mov_b64_e32 v[16:17], v[2:3]
	v_mov_b64_e32 v[18:19], v[2:3]
	v_mov_b64_e32 v[20:21], v[2:3]
	v_mov_b64_e32 v[22:23], v[2:3]
	v_mov_b64_e32 v[24:25], v[2:3]
	v_mov_b64_e32 v[26:27], v[2:3]
	v_mov_b64_e32 v[28:29], v[2:3]
	v_mov_b64_e32 v[30:31], v[2:3]
	v_mov_b64_e32 v[32:33], v[2:3]
	v_mov_b64_e32 v[34:35], v[2:3]
	v_mov_b64_e32 v[36:37], v[2:3]
	v_mov_b64_e32 v[38:39], v[2:3]
	v_mov_b64_e32 v[40:41], v[2:3]
	v_mov_b64_e32 v[42:43], v[2:3]
	v_mov_b64_e32 v[44:45], v[2:3]
	v_mov_b64_e32 v[46:47], v[2:3]
	v_mov_b64_e32 v[48:49], v[2:3]
	v_mov_b64_e32 v[50:51], v[2:3]
	v_mov_b64_e32 v[52:53], v[2:3]
	v_mov_b64_e32 v[54:55], v[2:3]
	v_mov_b64_e32 v[56:57], v[2:3]
	v_mov_b64_e32 v[58:59], v[2:3]
	v_mov_b64_e32 v[60:61], v[2:3]
	v_mov_b64_e32 v[62:63], v[2:3]
	v_mov_b64_e32 v[64:65], v[2:3]
	v_mov_b64_e32 v[66:67], v[2:3]
	v_mov_b64_e32 v[68:69], v[2:3]
	v_mov_b64_e32 v[70:71], v[2:3]
	v_mov_b64_e32 v[72:73], v[2:3]
	v_mov_b64_e32 v[74:75], v[2:3]
	v_mov_b64_e32 v[76:77], v[2:3]
	v_mov_b64_e32 v[78:79], v[2:3]
	v_mov_b64_e32 v[80:81], v[2:3]
	v_mov_b64_e32 v[82:83], v[2:3]
	v_mov_b64_e32 v[84:85], v[2:3]
	v_mov_b64_e32 v[86:87], v[2:3]
	v_mov_b64_e32 v[88:89], v[2:3]
	v_mov_b64_e32 v[90:91], v[2:3]
	v_mov_b64_e32 v[92:93], v[2:3]
	v_mov_b64_e32 v[94:95], v[2:3]
	v_mov_b64_e32 v[96:97], v[2:3]
	v_mov_b64_e32 v[98:99], v[2:3]
	v_mov_b64_e32 v[100:101], v[2:3]
	v_mov_b64_e32 v[102:103], v[2:3]
	v_mov_b64_e32 v[104:105], v[2:3]
	v_mov_b64_e32 v[106:107], v[2:3]
	v_mov_b64_e32 v[108:109], v[2:3]
	v_mov_b64_e32 v[110:111], v[2:3]
	v_mov_b64_e32 v[112:113], v[2:3]
	v_mov_b64_e32 v[114:115], v[2:3]
	v_mov_b64_e32 v[116:117], v[2:3]
	v_mov_b64_e32 v[118:119], v[2:3]
	v_mov_b64_e32 v[120:121], v[2:3]
	v_mov_b64_e32 v[122:123], v[2:3]
	v_mov_b64_e32 v[124:125], v[2:3]
	v_mov_b64_e32 v[126:127], v[2:3]
	v_mov_b64_e32 v[128:129], v[2:3]

; template <class Epi, class Sched, bool ALIGN_EPI = false, bool SP2 = false>
; __device__ __forceinline__ void gemm_phase(PG8_LAS unsigned char* lds, const Gemm g, const Sched& S, const Epi& E, int wave_s) {
;     ...
;         const bool has_next = S.next(ui + 1, nxt);
;         const char* nA = has_next ? (const char*)g.A + (size_t)nxt.pm * tstep : cA; const char* nB = has_next ? (const char*)g.Bt + (size_t)nxt.pn * tstep : cB;
;     ...
; #pragma unroll
;         for (int a = 0; a < 2; ++a)
; #pragma unroll
;             for (int b = 0; b < 2; ++b)
; #pragma unroll
;                 for (int m = 0; m < 4; ++m)
; #pragma unroll
;                     for (int n = 0; n < 2; ++n) acc[a][b][m][n] = (f32x4){0.f, 0.f, 0.f, 0.f};
;         cur = nxt; cA = nA; cB = nB; ++ui;
.LBB0_318:
	s_ashr_i32 s89, s88, 31
	s_lshl_b64 s[28:29], s[88:89], 19
	s_add_u32 s90, s41, s28
	s_addc_u32 s91, s42, s29
	s_and_b64 s[28:29], s[0:1], exec
	s_cselect_b32 s10, s91, s25
	s_cselect_b32 s31, s90, s24
	s_ashr_i32 s59, s58, 31
	s_lshl_b64 s[28:29], s[58:59], 19
	s_add_u32 s92, s43, s28
	s_addc_u32 s93, s44, s29
	s_and_b64 s[28:29], s[0:1], exec
	s_cselect_b32 s34, s93, s27
	s_cselect_b32 s35, s92, s26
	s_add_u32 s24, s24, 0x40080
	s_addc_u32 s25, s25, 0
	s_add_u32 s36, s26, 0x100
	v_mov_b32_e32 v2, 0
	s_addc_u32 s37, s27, 0
	s_mov_b32 s38, -2
	v_mov_b32_e32 v3, v2
	v_mov_b64_e32 v[4:5], v[2:3]
	v_mov_b64_e32 v[6:7], v[2:3]
	v_mov_b64_e32 v[8:9], v[2:3]
	v_mov_b64_e32 v[10:11], v[2:3]
	v_mov_b64_e32 v[12:13], v[2:3]
	v_mov_b64_e32 v[14:15], v[2:3]
	v_mov_b64_e32 v[16:17], v[2:3]
	v_mov_b64_e32 v[18:19], v[2:3]
	v_mov_b64_e32 v[20:21], v[2:3]
	v_mov_b64_e32 v[22:23], v[2:3]
	v_mov_b64_e32 v[24:25], v[2:3]
	v_mov_b64_e32 v[26:27], v[2:3]
	v_mov_b64_e32 v[28:29], v[2:3]
	v_mov_b64_e32 v[30:31], v[2:3]
	v_mov_b64_e32 v[32:33], v[2:3]
	v_mov_b64_e32 v[34:35], v[2:3]
	v_mov_b64_e32 v[36:37], v[2:3]
	v_mov_b64_e32 v[38:39], v[2:3]
	v_mov_b64_e32 v[40:41], v[2:3]
	v_mov_b64_e32 v[42:43], v[2:3]
	v_mov_b64_e32 v[44:45], v[2:3]
	v_mov_b64_e32 v[46:47], v[2:3]
	v_mov_b64_e32 v[48:49], v[2:3]
	v_mov_b64_e32 v[50:51], v[2:3]
	v_mov_b64_e32 v[52:53], v[2:3]
	v_mov_b64_e32 v[54:55], v[2:3]
	v_mov_b64_e32 v[56:57], v[2:3]
	v_mov_b64_e32 v[58:59], v[2:3]
	v_mov_b64_e32 v[60:61], v[2:3]
	v_mov_b64_e32 v[62:63], v[2:3]
	v_mov_b64_e32 v[64:65], v[2:3]
	v_mov_b64_e32 v[66:67], v[2:3]
	v_mov_b64_e32 v[68:69], v[2:3]
	v_mov_b64_e32 v[70:71], v[2:3]
	v_mov_b64_e32 v[72:73], v[2:3]
	v_mov_b64_e32 v[74:75], v[2:3]
	v_mov_b64_e32 v[76:77], v[2:3]
	v_mov_b64_e32 v[78:79], v[2:3]
	v_mov_b64_e32 v[80:81], v[2:3]
	v_mov_b64_e32 v[82:83], v[2:3]
	v_mov_b64_e32 v[84:85], v[2:3]
	v_mov_b64_e32 v[86:87], v[2:3]
	v_mov_b64_e32 v[88:89], v[2:3]
	v_mov_b64_e32 v[90:91], v[2:3]
	v_mov_b64_e32 v[92:93], v[2:3]
	v_mov_b64_e32 v[94:95], v[2:3]
	v_mov_b64_e32 v[96:97], v[2:3]
	v_mov_b64_e32 v[98:99], v[2:3]
	v_mov_b64_e32 v[100:101], v[2:3]
	v_mov_b64_e32 v[102:103], v[2:3]
	v_mov_b64_e32 v[104:105], v[2:3]
	v_mov_b64_e32 v[106:107], v[2:3]
	v_mov_b64_e32 v[108:109], v[2:3]
	v_mov_b64_e32 v[110:111], v[2:3]
	v_mov_b64_e32 v[112:113], v[2:3]
	v_mov_b64_e32 v[114:115], v[2:3]
	v_mov_b64_e32 v[116:117], v[2:3]
	v_mov_b64_e32 v[118:119], v[2:3]
	v_mov_b64_e32 v[120:121], v[2:3]
	v_mov_b64_e32 v[122:123], v[2:3]
	v_mov_b64_e32 v[124:125], v[2:3]
	v_mov_b64_e32 v[126:127], v[2:3]
	v_mov_b64_e32 v[128:129], v[2:3]

; template <class Epi, class Sched, bool ALIGN_EPI = false, bool SP2 = false>
; __device__ __forceinline__ void gemm_phase(PG8_LAS unsigned char* lds, const Gemm g, const Sched& S, const Epi& E, int wave_s) {
;     ...
;         const bool has_next = S.next(ui + 1, nxt);
;         const char* nA = has_next ? (const char*)g.A + (size_t)nxt.pm * tstep : cA; const char* nB = has_next ? (const char*)g.Bt + (size_t)nxt.pn * tstep : cB;
;     ...
; #pragma unroll
;         for (int a = 0; a < 2; ++a)
; #pragma unroll
;             for (int b = 0; b < 2; ++b)
; #pragma unroll
;                 for (int m = 0; m < 4; ++m)
; #pragma unroll
;                     for (int n = 0; n < 2; ++n) acc[a][b][m][n] = (f32x4){0.f, 0.f, 0.f, 0.f};
;         cur = nxt; cA = nA; cB = nB; ++ui;
.LBB0_742:
	s_ashr_i32 s89, s88, 31
	s_lshl_b64 s[28:29], s[88:89], s23
	s_add_u32 s90, s12, s28
	s_addc_u32 s91, s13, s29
	s_and_b64 s[28:29], s[0:1], exec
	s_cselect_b32 s28, s91, s25
	s_cselect_b32 s29, s90, s24
	s_ashr_i32 s73, s72, 31
	s_lshl_b64 s[70:71], s[72:73], s23
	s_add_u32 s92, s16, s70
	s_addc_u32 s93, s18, s71
	s_and_b64 s[70:71], s[0:1], exec
	s_cselect_b32 s45, s93, s27
	s_cselect_b32 s51, s92, s26
	s_add_u32 s24, s24, 0x80
	s_addc_u32 s25, s25, 0
	s_add_u32 s57, s26, 0x100
	v_mov_b32_e32 v2, 0
	s_addc_u32 s63, s27, 0
	s_mov_b32 s26, 0
	v_mov_b32_e32 v3, v2
	v_mov_b64_e32 v[4:5], v[2:3]
	v_mov_b64_e32 v[6:7], v[2:3]
	v_mov_b64_e32 v[8:9], v[2:3]
	v_mov_b64_e32 v[10:11], v[2:3]
	v_mov_b64_e32 v[12:13], v[2:3]
	v_mov_b64_e32 v[14:15], v[2:3]
	v_mov_b64_e32 v[16:17], v[2:3]
	v_mov_b64_e32 v[18:19], v[2:3]
	v_mov_b64_e32 v[20:21], v[2:3]
	v_mov_b64_e32 v[22:23], v[2:3]
	v_mov_b64_e32 v[24:25], v[2:3]
	v_mov_b64_e32 v[26:27], v[2:3]
	v_mov_b64_e32 v[28:29], v[2:3]
	v_mov_b64_e32 v[30:31], v[2:3]
	v_mov_b64_e32 v[32:33], v[2:3]
	v_mov_b64_e32 v[34:35], v[2:3]
	v_mov_b64_e32 v[36:37], v[2:3]
	v_mov_b64_e32 v[38:39], v[2:3]
	v_mov_b64_e32 v[40:41], v[2:3]
	v_mov_b64_e32 v[42:43], v[2:3]
	v_mov_b64_e32 v[44:45], v[2:3]
	v_mov_b64_e32 v[46:47], v[2:3]
	v_mov_b64_e32 v[48:49], v[2:3]
	v_mov_b64_e32 v[50:51], v[2:3]
	v_mov_b64_e32 v[52:53], v[2:3]
	v_mov_b64_e32 v[54:55], v[2:3]
	v_mov_b64_e32 v[56:57], v[2:3]
	v_mov_b64_e32 v[58:59], v[2:3]
	v_mov_b64_e32 v[60:61], v[2:3]
	v_mov_b64_e32 v[62:63], v[2:3]
	v_mov_b64_e32 v[64:65], v[2:3]
	v_mov_b64_e32 v[66:67], v[2:3]
	v_mov_b64_e32 v[68:69], v[2:3]
	v_mov_b64_e32 v[70:71], v[2:3]
	v_mov_b64_e32 v[72:73], v[2:3]
	v_mov_b64_e32 v[74:75], v[2:3]
	v_mov_b64_e32 v[76:77], v[2:3]
	v_mov_b64_e32 v[78:79], v[2:3]
	v_mov_b64_e32 v[80:81], v[2:3]
	v_mov_b64_e32 v[82:83], v[2:3]
	v_mov_b64_e32 v[84:85], v[2:3]
	v_mov_b64_e32 v[86:87], v[2:3]
	v_mov_b64_e32 v[88:89], v[2:3]
	v_mov_b64_e32 v[90:91], v[2:3]
	v_mov_b64_e32 v[92:93], v[2:3]
	v_mov_b64_e32 v[94:95], v[2:3]
	v_mov_b64_e32 v[96:97], v[2:3]
	v_mov_b64_e32 v[98:99], v[2:3]
	v_mov_b64_e32 v[100:101], v[2:3]
	v_mov_b64_e32 v[102:103], v[2:3]
	v_mov_b64_e32 v[104:105], v[2:3]
	v_mov_b64_e32 v[106:107], v[2:3]
	v_mov_b64_e32 v[108:109], v[2:3]
	v_mov_b64_e32 v[110:111], v[2:3]
	v_mov_b64_e32 v[112:113], v[2:3]
	v_mov_b64_e32 v[114:115], v[2:3]
	v_mov_b64_e32 v[116:117], v[2:3]
	v_mov_b64_e32 v[118:119], v[2:3]
	v_mov_b64_e32 v[120:121], v[2:3]
	v_mov_b64_e32 v[122:123], v[2:3]
	v_mov_b64_e32 v[124:125], v[2:3]
	v_mov_b64_e32 v[126:127], v[2:3]
	v_mov_b64_e32 v[128:129], v[2:3]

; template <class Epi, class Sched, bool ALIGN_EPI = false, bool SP2 = false>
; __device__ __forceinline__ void gemm_phase(PG8_LAS unsigned char* lds, const Gemm g, const Sched& S, const Epi& E, int wave_s) {
;     ...
;         const bool has_next = S.next(ui + 1, nxt);
;         const char* nA = has_next ? (const char*)g.A + (size_t)nxt.pm * tstep : cA; const char* nB = has_next ? (const char*)g.Bt + (size_t)nxt.pn * tstep : cB;
;     ...
; #pragma unroll
;         for (int a = 0; a < 2; ++a)
; #pragma unroll
;             for (int b = 0; b < 2; ++b)
; #pragma unroll
;                 for (int m = 0; m < 4; ++m)
; #pragma unroll
;                     for (int n = 0; n < 2; ++n) acc[a][b][m][n] = (f32x4){0.f, 0.f, 0.f, 0.f};
;         cur = nxt; cA = nA; cB = nB; ++ui;
.LBB0_917:
	s_ashr_i32 s89, s88, 31
	s_lshl_b64 s[28:29], s[88:89], 19
	s_add_u32 s90, s12, s28
	s_addc_u32 s91, s13, s29
	s_and_b64 s[28:29], s[0:1], exec
	s_cselect_b32 s41, s91, s25
	s_cselect_b32 s42, s90, s24
	s_ashr_i32 s87, s86, 31
	s_lshl_b64 s[28:29], s[86:87], 19
	s_add_u32 s92, s16, s28
	s_addc_u32 s93, s18, s29
	s_and_b64 s[28:29], s[0:1], exec
	s_cselect_b32 s43, s93, s27
	s_cselect_b32 s44, s92, s26
	s_add_u32 s24, s24, 0x40080
	s_addc_u32 s25, s25, 0
	s_add_u32 s45, s26, 0x100
	v_mov_b32_e32 v2, 0
	s_addc_u32 s51, s27, 0
	s_mov_b32 s57, -2
	v_mov_b32_e32 v3, v2
	v_mov_b64_e32 v[4:5], v[2:3]
	v_mov_b64_e32 v[6:7], v[2:3]
	v_mov_b64_e32 v[8:9], v[2:3]
	v_mov_b64_e32 v[10:11], v[2:3]
	v_mov_b64_e32 v[12:13], v[2:3]
	v_mov_b64_e32 v[14:15], v[2:3]
	v_mov_b64_e32 v[16:17], v[2:3]
	v_mov_b64_e32 v[18:19], v[2:3]
	v_mov_b64_e32 v[20:21], v[2:3]
	v_mov_b64_e32 v[22:23], v[2:3]
	v_mov_b64_e32 v[24:25], v[2:3]
	v_mov_b64_e32 v[26:27], v[2:3]
	v_mov_b64_e32 v[28:29], v[2:3]
	v_mov_b64_e32 v[30:31], v[2:3]
	v_mov_b64_e32 v[32:33], v[2:3]
	v_mov_b64_e32 v[34:35], v[2:3]
	v_mov_b64_e32 v[36:37], v[2:3]
	v_mov_b64_e32 v[38:39], v[2:3]
	v_mov_b64_e32 v[40:41], v[2:3]
	v_mov_b64_e32 v[42:43], v[2:3]
	v_mov_b64_e32 v[44:45], v[2:3]
	v_mov_b64_e32 v[46:47], v[2:3]
	v_mov_b64_e32 v[48:49], v[2:3]
	v_mov_b64_e32 v[50:51], v[2:3]
	v_mov_b64_e32 v[52:53], v[2:3]
	v_mov_b64_e32 v[54:55], v[2:3]
	v_mov_b64_e32 v[56:57], v[2:3]
	v_mov_b64_e32 v[58:59], v[2:3]
	v_mov_b64_e32 v[60:61], v[2:3]
	v_mov_b64_e32 v[62:63], v[2:3]
	v_mov_b64_e32 v[64:65], v[2:3]
	v_mov_b64_e32 v[66:67], v[2:3]
	v_mov_b64_e32 v[68:69], v[2:3]
	v_mov_b64_e32 v[70:71], v[2:3]
	v_mov_b64_e32 v[72:73], v[2:3]
	v_mov_b64_e32 v[74:75], v[2:3]
	v_mov_b64_e32 v[76:77], v[2:3]
	v_mov_b64_e32 v[78:79], v[2:3]
	v_mov_b64_e32 v[80:81], v[2:3]
	v_mov_b64_e32 v[82:83], v[2:3]
	v_mov_b64_e32 v[84:85], v[2:3]
	v_mov_b64_e32 v[86:87], v[2:3]
	v_mov_b64_e32 v[88:89], v[2:3]
	v_mov_b64_e32 v[90:91], v[2:3]
	v_mov_b64_e32 v[92:93], v[2:3]
	v_mov_b64_e32 v[94:95], v[2:3]
	v_mov_b64_e32 v[96:97], v[2:3]
	v_mov_b64_e32 v[98:99], v[2:3]
	v_mov_b64_e32 v[100:101], v[2:3]
	v_mov_b64_e32 v[102:103], v[2:3]
	v_mov_b64_e32 v[104:105], v[2:3]
	v_mov_b64_e32 v[106:107], v[2:3]
	v_mov_b64_e32 v[108:109], v[2:3]
	v_mov_b64_e32 v[110:111], v[2:3]
	v_mov_b64_e32 v[112:113], v[2:3]
	v_mov_b64_e32 v[114:115], v[2:3]
	v_mov_b64_e32 v[116:117], v[2:3]
	v_mov_b64_e32 v[118:119], v[2:3]
	v_mov_b64_e32 v[120:121], v[2:3]
	v_mov_b64_e32 v[122:123], v[2:3]
	v_mov_b64_e32 v[124:125], v[2:3]
	v_mov_b64_e32 v[126:127], v[2:3]
	v_mov_b64_e32 v[128:129], v[2:3]

; template <class Epi, class Sched, bool ALIGN_EPI = false, bool SP2 = false>
; __device__ __forceinline__ void gemm_phase(PG8_LAS unsigned char* lds, const Gemm g, const Sched& S, const Epi& E, int wave_s) {
;     ...
;         const bool has_next = S.next(ui + 1, nxt);
;         const char* nA = has_next ? (const char*)g.A + (size_t)nxt.pm * tstep : cA; const char* nB = has_next ? (const char*)g.Bt + (size_t)nxt.pn * tstep : cB;
;     ...
; #pragma unroll
;         for (int a = 0; a < 2; ++a)
; #pragma unroll
;             for (int b = 0; b < 2; ++b)
; #pragma unroll
;                 for (int m = 0; m < 4; ++m)
; #pragma unroll
;                     for (int n = 0; n < 2; ++n) acc[a][b][m][n] = (f32x4){0.f, 0.f, 0.f, 0.f};
;         cur = nxt; cA = nA; cB = nB; ++ui;
.LBB0_985:
	s_ashr_i32 s87, s86, 31
	s_lshl_b64 s[28:29], s[86:87], 21
	s_add_u32 s88, s10, s28
	s_addc_u32 s89, s12, s29
	s_and_b64 s[28:29], s[0:1], exec
	s_cselect_b32 s41, s89, s25
	s_cselect_b32 s42, s88, s24
	s_ashr_i32 s73, s72, 31
	s_lshl_b64 s[28:29], s[72:73], 21
	s_add_u32 s90, s13, s28
	s_addc_u32 s91, s16, s29
	s_and_b64 s[28:29], s[0:1], exec
	s_cselect_b32 s43, s91, s27
	s_cselect_b32 s44, s90, s26
	s_add_u32 s24, s24, 0x100080
	s_addc_u32 s25, s25, 0
	s_add_u32 s45, s26, 0x100
	v_mov_b32_e32 v2, 0
	s_addc_u32 s51, s27, 0
	s_mov_b32 s57, -2
	v_mov_b32_e32 v3, v2
	v_mov_b64_e32 v[4:5], v[2:3]
	v_mov_b64_e32 v[6:7], v[2:3]
	v_mov_b64_e32 v[8:9], v[2:3]
	v_mov_b64_e32 v[10:11], v[2:3]
	v_mov_b64_e32 v[12:13], v[2:3]
	v_mov_b64_e32 v[14:15], v[2:3]
	v_mov_b64_e32 v[16:17], v[2:3]
	v_mov_b64_e32 v[18:19], v[2:3]
	v_mov_b64_e32 v[20:21], v[2:3]
	v_mov_b64_e32 v[22:23], v[2:3]
	v_mov_b64_e32 v[24:25], v[2:3]
	v_mov_b64_e32 v[26:27], v[2:3]
	v_mov_b64_e32 v[28:29], v[2:3]
	v_mov_b64_e32 v[30:31], v[2:3]
	v_mov_b64_e32 v[32:33], v[2:3]
	v_mov_b64_e32 v[34:35], v[2:3]
	v_mov_b64_e32 v[36:37], v[2:3]
	v_mov_b64_e32 v[38:39], v[2:3]
	v_mov_b64_e32 v[40:41], v[2:3]
	v_mov_b64_e32 v[42:43], v[2:3]
	v_mov_b64_e32 v[44:45], v[2:3]
	v_mov_b64_e32 v[46:47], v[2:3]
	v_mov_b64_e32 v[48:49], v[2:3]
	v_mov_b64_e32 v[50:51], v[2:3]
	v_mov_b64_e32 v[52:53], v[2:3]
	v_mov_b64_e32 v[54:55], v[2:3]
	v_mov_b64_e32 v[56:57], v[2:3]
	v_mov_b64_e32 v[58:59], v[2:3]
	v_mov_b64_e32 v[60:61], v[2:3]
	v_mov_b64_e32 v[62:63], v[2:3]
	v_mov_b64_e32 v[64:65], v[2:3]
	v_mov_b64_e32 v[66:67], v[2:3]
	v_mov_b64_e32 v[68:69], v[2:3]
	v_mov_b64_e32 v[70:71], v[2:3]
	v_mov_b64_e32 v[72:73], v[2:3]
	v_mov_b64_e32 v[74:75], v[2:3]
	v_mov_b64_e32 v[76:77], v[2:3]
	v_mov_b64_e32 v[78:79], v[2:3]
	v_mov_b64_e32 v[80:81], v[2:3]
	v_mov_b64_e32 v[82:83], v[2:3]
	v_mov_b64_e32 v[84:85], v[2:3]
	v_mov_b64_e32 v[86:87], v[2:3]
	v_mov_b64_e32 v[88:89], v[2:3]
	v_mov_b64_e32 v[90:91], v[2:3]
	v_mov_b64_e32 v[92:93], v[2:3]
	v_mov_b64_e32 v[94:95], v[2:3]
	v_mov_b64_e32 v[96:97], v[2:3]
	v_mov_b64_e32 v[98:99], v[2:3]
	v_mov_b64_e32 v[100:101], v[2:3]
	v_mov_b64_e32 v[102:103], v[2:3]
	v_mov_b64_e32 v[104:105], v[2:3]
	v_mov_b64_e32 v[106:107], v[2:3]
	v_mov_b64_e32 v[108:109], v[2:3]
	v_mov_b64_e32 v[110:111], v[2:3]
	v_mov_b64_e32 v[112:113], v[2:3]
	v_mov_b64_e32 v[114:115], v[2:3]
	v_mov_b64_e32 v[116:117], v[2:3]
	v_mov_b64_e32 v[118:119], v[2:3]
	v_mov_b64_e32 v[120:121], v[2:3]
	v_mov_b64_e32 v[122:123], v[2:3]
	v_mov_b64_e32 v[124:125], v[2:3]
	v_mov_b64_e32 v[126:127], v[2:3]
	v_mov_b64_e32 v[128:129], v[2:3]
